# deferred copies rebalanced: all w_out copies stay in P0b (idle non-GEMM workgroups), only w_in of layers 1..3 goes to the scan phase
# baseline (speedup 1.0000x reference)
; #define LAS __attribute__((address_space(3)))
; __global__ void __launch_bounds__(512, 2) mega(Args a) {
;     ...
;         LAS float* scr = (LAS float*)(lds + wave * 16384);
;         const int it0 = bx < NGEMM ? N1 + bx * 8 + wave : (bx - NGEMM) * 8 + wave, itN = bx < NGEMM ? NIT2 : N1, its = bx < NGEMM ? NGEMM * 8 : (G - NGEMM) * 8;
; #pragma unroll 1
;         for (int it = it0; it < itN; it += its) {
.LBB0_148:
	s_movk_i32 s4, 0xfd00
	s_mov_b32 s14, 0x4020
	s_movk_i32 s15, 0x500
	s_branch .LBB0_150

; #define LAS __attribute__((address_space(3)))
; __device__ __forceinline__ void transpose_item(const float* W, int K, int N, bf16_t* WT, LAS float* scr, int item, int lane) {
;     const int nblk = (N + 31) / 32, kb = item / nblk, nb = item % nblk, k0 = 64 * kb, n0 = 32 * nb;
;     const int nn = n0 + (lane & 31); const bool ok = nn < N;
;     float v[32];
; #pragma unroll
;     for (int i = 0; i < 32; ++i) { const int kk = 2 * i + (lane >> 5); v[i] = ok ? W[(size_t)(k0 + kk) * N + nn] : 0.f; }
; #pragma unroll
;     for (int i = 0; i < 32; ++i) { const int kk = 2 * i + (lane >> 5); scr[kk * 33 + (lane & 31)] = v[i]; }
; __global__ void __launch_bounds__(512, 2) mega(Args a) {
;     ...
;         for (int it = it0; it < itN; it += its) {
;             int r = it;
;             if (r < 4 * I_IN) { const int l = r / I_IN; r -= l * I_IN; transpose_item(((const float*)ap->in[10]) + (size_t)l * DM * DIN, DM, DIN, WSP(bf16_t, WS_WIN) + (size_t)l * DINP * DM, scr, r, lane); }
;             else { r -= 4 * I_IN; const int l = r / I_OUT; r -= l * I_OUT; transpose_item(((const float*)ap->in[16]) + (size_t)l * DM * DM, DM, DM, WSP(bf16_t, WS_WOUT) + (size_t)l * DM * DM, scr, r, lane); }
.LBB0_513:
	s_or_b64 exec, exec, s[4:5]
	s_mov_b64 exec, -1
	s_waitcnt vmcnt(0) lgkmcnt(0)
	s_cmp_gt_u32 s92, 2
	s_cbranch_scc1 .Lp4t_skip
	s_load_dwordx2 s[22:23], s[0:1], 0x50
	s_load_dwordx2 s[24:25], s[0:1], 0x80
	s_load_dwordx2 s[26:27], s[0:1], 0x98
	s_lshr_b32 s38, s3, 6
	s_lshl_b32 s6, s38, 14
	v_mbcnt_lo_u32_b32 v24, -1, 0
	v_mbcnt_hi_u32_b32 v24, -1, v24
	v_and_b32_e32 v18, 63, v24
	v_and_b32_e32 v19, 31, v18
	v_lshrrev_b32_e32 v20, 5, v18
	v_xor_b32_e32 v2, 0, v19
	v_lshlrev_b32_e32 v2, 2, v2
	v_xor_b32_e32 v3, 8, v19
	v_lshlrev_b32_e32 v3, 2, v3
	v_xor_b32_e32 v4, 16, v19
	v_lshlrev_b32_e32 v4, 2, v4
	v_xor_b32_e32 v5, 24, v19
	v_lshlrev_b32_e32 v5, 2, v5
	v_mov_b32_e32 v0, v20
	v_and_b32_e32 v19, 7, v18
	v_lshrrev_b32_e32 v20, 3, v18
	v_and_b32_e32 v21, 3, v19
	v_lshlrev_b32_e32 v22, 10, v19
	v_lshl_add_u32 v22, s38, 14, v22
	v_xor_b32_e32 v23, 0, v21
	v_lshl_add_u32 v23, v23, 3, v20
	v_lshl_add_u32 v62, v23, 2, v22
	v_xor_b32_e32 v23, 1, v21
	v_lshl_add_u32 v23, v23, 3, v20
	v_lshl_add_u32 v63, v23, 2, v22
	v_xor_b32_e32 v23, 2, v21
	v_lshl_add_u32 v23, v23, 3, v20
	v_lshl_add_u32 v64, v23, 2, v22
	v_xor_b32_e32 v23, 3, v21
	v_lshl_add_u32 v23, v23, 3, v20
	v_lshl_add_u32 v65, v23, 2, v22
	v_lshlrev_b32_e32 v23, 12, v20
	v_lshl_add_u32 v13, v19, 4, v23
	v_add_u32_e32 v14, 0x8000, v13
	v_add_u32_e32 v15, 0x10000, v13
	v_add_u32_e32 v16, 0x18000, v13
	s_sub_u32 s4, s2, 64
	s_lshl_b32 s4, s4, 3
	s_add_u32 s4, s4, s38
	s_movk_i32 s16, 0x2020
	s_movk_i32 s18, 0x600
	s_add_u32 s70, s92, 1
	s_mul_i32 s98, s70, 0x2020
	s_lshl_b32 s99, s70, 11
	s_addk_i32 s99, 0x6060
	s_waitcnt lgkmcnt(0)
	s_mov_b32 s7, s4
	s_cmp_ge_u32 s7, 0x2020
	s_cselect_b32 s70, s99, s98
	s_add_u32 s7, s7, s70
	s_cmp_ge_u32 s7, 0x8080
	s_cbranch_scc1 .Lp4t_la_p0_out
	s_mul_hi_u32 s38, s7, 0x7f808
	s_mul_i32 s70, s38, 0x2020
	s_sub_u32 s7, s7, s70
	s_mul_hi_u32 s55, s7, 0xff0100
	s_mul_i32 s70, s55, 0x101
	s_sub_u32 s7, s7, s70
	s_mul_i32 s70, s38, 0x4020000
	s_mul_i32 s71, s55, 0x201000
	s_add_u32 s70, s70, s71
	s_lshl_b32 s71, s7, 7
	s_add_u32 s70, s70, s71
	s_add_u32 s28, s22, s70
	s_addc_u32 s29, s23, 0
	s_mov_b32 s19, 0x8040
	s_mov_b32 s32, 0x10080
	s_mov_b64 s[34:35], -1
	s_mov_b64 s[36:37], -1
	s_cmp_eq_u32 s7, 0x100
	s_cbranch_scc0 .Lp4t_la_p0_done
	s_mov_b32 s34, 0xffff
	s_mov_b32 s35, 0xffff
	s_mov_b32 s36, 0xffff0000
	s_mov_b32 s37, 0xffff0000
	s_branch .Lp4t_la_p0_done
